# v59 + MoBA block selection loop: the 16 block-mean LDS reads kept 7 deep in flight instead of 10 serialized round trips, scalar fma chain without the v_mov shuffles (bit-identical sums)
# speedup vs baseline: 1.0168x; 1.0060x over previous
; #define LAS __attribute__((address_space(3)))
; template <bool MOBA>
; __device__ __forceinline__ void attn_unit(unsigned char* lds, LAS unsigned char* lds3, const Params& p, int b, int h, int qb) {
;     ...
;             for (int j = 0; j < qb; ++j) { float d = 0.f;
; #pragma unroll
;                 for (int c = 0; c < 16; ++c) { const f32x4 kv = *(const LAS f32x4*)(kms + j * 64 + c * 4); d += qv[4 * c] * kv[0] + qv[4 * c + 1] * kv[1] + qv[4 * c + 2] * kv[2] + qv[4 * c + 3] * kv[3]; }
;                 if (d > v1) { v3 = v2; i3 = i2; v2 = v1; i2 = i1; v1 = d; i1 = j; } else if (d > v2) { v3 = v2; i3 = i2; v2 = d; i2 = j; } else if (d > v3) { v3 = d; i3 = j; } }
.LBB0_387:
	s_add_i32 s6, s4, 0x12000
	v_mov_b32_e32 v154, s6
	ds_read_b128 v[212:215], v154
	ds_read_b128 v[216:219], v154 offset:16
	ds_read_b128 v[220:223], v154 offset:32
	ds_read_b128 v[236:239], v154 offset:48
	ds_read_b128 v[240:243], v154 offset:64
	ds_read_b128 v[244:247], v154 offset:80
	ds_read_b128 v[248:251], v154 offset:96
	s_waitcnt lgkmcnt(6)
	v_mul_f32_e32 v158, v213, v133
	v_fmac_f32_e32 v158, v212, v105
	v_fmac_f32_e32 v158, v214, v134
	v_fmac_f32_e32 v158, v215, v135
	ds_read_b128 v[212:215], v154 offset:112
	v_add_f32_e32 v164, 0, v158
	s_waitcnt lgkmcnt(6)
	v_mul_f32_e32 v158, v217, v137
	v_fmac_f32_e32 v158, v216, v136
	v_fmac_f32_e32 v158, v218, v138
	v_fmac_f32_e32 v158, v219, v139
	ds_read_b128 v[216:219], v154 offset:128
	v_add_f32_e32 v164, v164, v158
	s_waitcnt lgkmcnt(6)
	v_mul_f32_e32 v158, v221, v141
	v_fmac_f32_e32 v158, v220, v140
	v_fmac_f32_e32 v158, v222, v142
	v_fmac_f32_e32 v158, v223, v143
	ds_read_b128 v[220:223], v154 offset:144
	v_add_f32_e32 v164, v164, v158
	s_waitcnt lgkmcnt(6)
	v_mul_f32_e32 v158, v237, v145
	v_fmac_f32_e32 v158, v236, v144
	v_fmac_f32_e32 v158, v238, v146
	v_fmac_f32_e32 v158, v239, v147
	ds_read_b128 v[236:239], v154 offset:160
	v_add_f32_e32 v164, v164, v158
	s_waitcnt lgkmcnt(6)
	v_mul_f32_e32 v158, v241, v44
	v_fmac_f32_e32 v158, v240, v42
	v_fmac_f32_e32 v158, v242, v46
	v_fmac_f32_e32 v158, v243, v48
	ds_read_b128 v[240:243], v154 offset:176
	v_add_f32_e32 v164, v164, v158
	s_waitcnt lgkmcnt(6)
	v_mul_f32_e32 v158, v245, v45
	v_fmac_f32_e32 v158, v244, v43
	v_fmac_f32_e32 v158, v246, v47
	v_fmac_f32_e32 v158, v247, v49
	ds_read_b128 v[244:247], v154 offset:192
	v_add_f32_e32 v164, v164, v158
	s_waitcnt lgkmcnt(6)
	v_mul_f32_e32 v158, v249, v52
	v_fmac_f32_e32 v158, v248, v50
	v_fmac_f32_e32 v158, v250, v54
	v_fmac_f32_e32 v158, v251, v56
	ds_read_b128 v[248:251], v154 offset:208
	v_add_f32_e32 v164, v164, v158
	s_waitcnt lgkmcnt(6)
	v_mul_f32_e32 v158, v213, v53
	v_fmac_f32_e32 v158, v212, v51
	v_fmac_f32_e32 v158, v214, v55
	v_fmac_f32_e32 v158, v215, v57
	ds_read_b128 v[212:215], v154 offset:224
	v_add_f32_e32 v164, v164, v158
	s_waitcnt lgkmcnt(6)
	v_mul_f32_e32 v158, v217, v60
	v_fmac_f32_e32 v158, v216, v58
	v_fmac_f32_e32 v158, v218, v62
	v_fmac_f32_e32 v158, v219, v64
	ds_read_b128 v[216:219], v154 offset:240
	v_add_f32_e32 v164, v164, v158
	s_waitcnt lgkmcnt(6)
	v_mul_f32_e32 v158, v221, v61
	v_fmac_f32_e32 v158, v220, v59
	v_fmac_f32_e32 v158, v222, v63
	v_fmac_f32_e32 v158, v223, v65
	v_add_f32_e32 v164, v164, v158
	s_waitcnt lgkmcnt(5)
	v_mul_f32_e32 v158, v237, v68
	v_fmac_f32_e32 v158, v236, v66
	v_fmac_f32_e32 v158, v238, v70
	v_fmac_f32_e32 v158, v239, v72
	v_add_f32_e32 v164, v164, v158
	s_waitcnt lgkmcnt(4)
	v_mul_f32_e32 v158, v241, v69
	v_fmac_f32_e32 v158, v240, v67
	v_fmac_f32_e32 v158, v242, v71
	v_fmac_f32_e32 v158, v243, v73
	v_add_f32_e32 v164, v164, v158
	s_waitcnt lgkmcnt(3)
	v_mul_f32_e32 v158, v245, v76
	v_fmac_f32_e32 v158, v244, v74
	v_fmac_f32_e32 v158, v246, v78
	v_fmac_f32_e32 v158, v247, v80
	v_add_f32_e32 v164, v164, v158
	s_waitcnt lgkmcnt(2)
	v_mul_f32_e32 v158, v249, v77
	v_fmac_f32_e32 v158, v248, v75
	v_fmac_f32_e32 v158, v250, v79
	v_fmac_f32_e32 v158, v251, v81
	v_add_f32_e32 v164, v164, v158
	s_waitcnt lgkmcnt(1)
	v_mul_f32_e32 v158, v213, v84
	v_fmac_f32_e32 v158, v212, v82
	v_fmac_f32_e32 v158, v214, v86
	v_fmac_f32_e32 v158, v215, v88
	v_add_f32_e32 v164, v164, v158
	s_waitcnt lgkmcnt(0)
	v_mul_f32_e32 v158, v217, v85
	v_fmac_f32_e32 v158, v216, v83
	v_fmac_f32_e32 v158, v218, v87
	v_fmac_f32_e32 v158, v219, v89
	v_add_f32_e32 v155, v164, v158
	v_mov_b32_e32 v156, s5
	v_cmp_ngt_f32_e32 vcc, v155, v149
	v_mov_b32_e32 v154, v152
	v_mov_b32_e32 v157, v149
	s_and_saveexec_b64 s[6:7], vcc
	s_cbranch_execz .LBB0_393
	v_cmp_ngt_f32_e32 vcc, v155, v151
	v_mov_b32_e32 v154, s5
	s_and_saveexec_b64 s[12:13], vcc
	s_cbranch_execz .LBB0_392
	v_cmp_gt_f32_e32 vcc, v155, v153
	s_and_saveexec_b64 s[14:15], vcc
	v_mov_b32_e32 v148, s5
	v_mov_b32_e32 v153, v155
	s_or_b64 exec, exec, s[14:15]
	v_mov_b32_e32 v155, v151
	v_mov_b32_e32 v151, v153
	v_mov_b32_e32 v154, v150
	v_mov_b32_e32 v150, v148
